# v7 + FFN1 meta-row skinny GEMM: all weight fragment loads of a task in flight at once, meta-row fragments loaded once per wave
# baseline (speedup 1.0000x reference)
.LBB0_118:
	s_or_b64 exec, exec, s[2:3]
	s_mov_b64 s[2:3], s[90:91]
	s_cmpk_gt_i32 s22, 0x2af
	s_barrier
	v_mbcnt_lo_u32_b32 v1, -1, 0
	v_mbcnt_hi_u32_b32 v1, -1, v1
	s_cbranch_scc1 .LBB0_123
	s_load_dwordx2 s[4:5], s[2:3], 0xc8
	v_and_b32_e32 v2, 15, v1
	v_and_b32_e32 v0, -16, v1
	v_lshlrev_b32_e32 v3, 13, v2
	v_or_b32_e32 v68, 0x4000, v2
	s_waitcnt lgkmcnt(0)
	s_add_u32 s8, s4, 0x800000
	s_addc_u32 s9, s5, 0
	s_lshl_b32 s0, s81, 10
	s_lshl_b32 s10, s81, 11
	s_cmp_lt_u32 s61, 64
	v_lshl_add_u32 v70, v1, 4, 0
	v_add3_u32 v0, v0, s0, v3
	s_cselect_b64 s[2:3], -1, 0
	v_ashrrev_i32_e32 v1, 2, v1
	v_lshlrev_b32_e32 v2, 13, v68
	v_mov_b32_e32 v3, 0
	s_add_u32 s6, s4, 0x27600000
	v_and_b32_e32 v71, -4, v1
	v_mov_b32_e32 v1, v3
	s_waitcnt vmcnt(4)
	v_add_u32_e32 v4, 64, v0
	v_mov_b32_e32 v5, v3
	v_add_u32_e32 v6, 0x80, v0
	v_mov_b32_e32 v7, v3
	v_add_u32_e32 v8, 0xc0, v0
	v_mov_b32_e32 v9, v3
	v_add_u32_e32 v10, 0x100, v0
	v_mov_b32_e32 v11, v3
	v_add_u32_e32 v12, 0x140, v0
	v_mov_b32_e32 v13, v3
	v_add_u32_e32 v14, 0x180, v0
	v_mov_b32_e32 v15, v3
	v_add_u32_e32 v16, 0x1c0, v0
	v_mov_b32_e32 v17, v3
	v_add_u32_e32 v18, 0x200, v0
	v_mov_b32_e32 v19, v3
	v_add_u32_e32 v20, 0x240, v0
	v_mov_b32_e32 v21, v3
	v_add_u32_e32 v22, 0x280, v0
	v_mov_b32_e32 v23, v3
	v_add_u32_e32 v24, 0x2c0, v0
	v_mov_b32_e32 v25, v3
	v_add_u32_e32 v26, 0x300, v0
	v_mov_b32_e32 v27, v3
	v_add_u32_e32 v28, 0x340, v0
	v_mov_b32_e32 v29, v3
	v_add_u32_e32 v30, 0x380, v0
	v_mov_b32_e32 v31, v3
	v_add_u32_e32 v32, 0x3c0, v0
	v_mov_b32_e32 v33, v3
	s_addc_u32 s7, s5, 0
	v_lshl_add_u64 v[66:67], s[4:5], 0, v[2:3]
	v_lshlrev_b32_e32 v2, 2, v68
	v_lshl_add_u64 v[34:35], s[6:7], 0, v[0:1]
	v_lshl_add_u64 v[36:37], s[6:7], 0, v[4:5]
	v_lshl_add_u64 v[38:39], s[6:7], 0, v[6:7]
	v_lshl_add_u64 v[40:41], s[6:7], 0, v[8:9]
	v_lshl_add_u64 v[42:43], s[6:7], 0, v[10:11]
	v_lshl_add_u64 v[44:45], s[6:7], 0, v[12:13]
	v_lshl_add_u64 v[46:47], s[6:7], 0, v[14:15]
	v_lshl_add_u64 v[48:49], s[6:7], 0, v[16:17]
	v_lshl_add_u64 v[50:51], s[6:7], 0, v[18:19]
	v_lshl_add_u64 v[52:53], s[6:7], 0, v[20:21]
	v_lshl_add_u64 v[54:55], s[6:7], 0, v[22:23]
	v_lshl_add_u64 v[56:57], s[6:7], 0, v[24:25]
	v_lshl_add_u64 v[58:59], s[6:7], 0, v[26:27]
	v_lshl_add_u64 v[60:61], s[6:7], 0, v[28:29]
	v_lshl_add_u64 v[62:63], s[6:7], 0, v[30:31]
	v_lshl_add_u64 v[64:65], s[6:7], 0, v[32:33]
	s_mov_b64 s[6:7], 0x2fa00000
	v_lshl_add_u64 v[68:69], s[4:5], 0, v[2:3]
	s_mov_b64 s[4:5], 0x600000
	v_lshl_add_u64 v[66:67], v[66:67], 0, s[6:7]
	v_lshl_add_u64 v[68:69], v[68:69], 0, s[4:5]
	s_lshl_b32 s11, s22, 4
	s_lshl_b32 s12, s72, 4
	s_lshl_b32 s13, s22, 5
	s_lshl_b32 s14, s72, 5
	s_movk_i32 s15, 0x7fff
	s_mov_b32 s16, 0x8200000
	v_mov_b32_e32 v72, 1
	s_mov_b32 s17, s22
	global_load_dwordx4 v[4:7], v[34:35], off
	global_load_dwordx4 v[8:11], v[34:35], off offset:64
	global_load_dwordx4 v[12:15], v[34:35], off offset:128
	global_load_dwordx4 v[16:19], v[34:35], off offset:192
	global_load_dwordx4 v[20:23], v[34:35], off offset:256
	global_load_dwordx4 v[24:27], v[34:35], off offset:320
	global_load_dwordx4 v[28:31], v[34:35], off offset:384
	global_load_dwordx4 v[36:39], v[34:35], off offset:448
	global_load_dwordx4 v[40:43], v[34:35], off offset:512
	global_load_dwordx4 v[44:47], v[34:35], off offset:576
	global_load_dwordx4 v[48:51], v[34:35], off offset:640
	global_load_dwordx4 v[52:55], v[34:35], off offset:704
	global_load_dwordx4 v[56:59], v[34:35], off offset:768
	global_load_dwordx4 v[60:63], v[34:35], off offset:832
	global_load_dwordx4 v[246:249], v[34:35], off offset:896
	global_load_dwordx4 v[250:253], v[34:35], off offset:960
	s_branch .LBB0_121

.LBB0_121:
	s_and_b32 s0, s13, 0xffffff00
	s_and_b32 s1, s11, 0x70
	s_or_b32 s4, s0, s1
	s_ashr_i32 s5, s4, 31
	s_lshl_b64 s[4:5], s[4:5], 13
	s_add_u32 s4, s8, s4
	s_addc_u32 s5, s9, s5
	s_add_u32 s6, s4, 0x100000
	s_addc_u32 s7, s5, 0
	v_lshl_add_u64 v[32:33], s[4:5], 0, v[0:1]
	v_lshl_add_u64 v[64:65], s[6:7], 0, v[0:1]
	v_add_u32_e32 v2, s10, v70
	s_andn2_b64 vcc, exec, s[2:3]
	global_load_dwordx4 v[82:85], v[32:33], off
	global_load_dwordx4 v[86:89], v[64:65], off
	global_load_dwordx4 v[90:93], v[32:33], off offset:64
	global_load_dwordx4 v[94:97], v[64:65], off offset:64
	global_load_dwordx4 v[98:101], v[32:33], off offset:128
	global_load_dwordx4 v[102:105], v[64:65], off offset:128
	global_load_dwordx4 v[106:109], v[32:33], off offset:192
	global_load_dwordx4 v[110:113], v[64:65], off offset:192
	global_load_dwordx4 v[114:117], v[32:33], off offset:256
	global_load_dwordx4 v[118:121], v[64:65], off offset:256
	global_load_dwordx4 v[122:125], v[32:33], off offset:320
	global_load_dwordx4 v[126:129], v[64:65], off offset:320
	global_load_dwordx4 v[130:133], v[32:33], off offset:384
	global_load_dwordx4 v[134:137], v[64:65], off offset:384
	global_load_dwordx4 v[138:141], v[32:33], off offset:448
	global_load_dwordx4 v[142:145], v[64:65], off offset:448
	global_load_dwordx4 v[146:149], v[32:33], off offset:512
	global_load_dwordx4 v[150:153], v[64:65], off offset:512
	global_load_dwordx4 v[154:157], v[32:33], off offset:576
	global_load_dwordx4 v[158:161], v[64:65], off offset:576
	global_load_dwordx4 v[162:165], v[32:33], off offset:640
	global_load_dwordx4 v[166:169], v[64:65], off offset:640
	global_load_dwordx4 v[170:173], v[32:33], off offset:704
	global_load_dwordx4 v[174:177], v[64:65], off offset:704
	global_load_dwordx4 v[178:181], v[32:33], off offset:768
	global_load_dwordx4 v[182:185], v[64:65], off offset:768
	global_load_dwordx4 v[186:189], v[32:33], off offset:832
	global_load_dwordx4 v[190:193], v[64:65], off offset:832
	global_load_dwordx4 v[194:197], v[32:33], off offset:896
	global_load_dwordx4 v[198:201], v[64:65], off offset:896
	global_load_dwordx4 v[202:205], v[32:33], off offset:960
	global_load_dwordx4 v[206:209], v[64:65], off offset:960
	s_waitcnt vmcnt(30)
	v_mfma_f32_16x16x32_bf16 v[74:77], v[82:85], v[4:7], 0
	v_mfma_f32_16x16x32_bf16 v[78:81], v[86:89], v[4:7], 0
	s_waitcnt vmcnt(28)
	v_mfma_f32_16x16x32_bf16 v[74:77], v[90:93], v[8:11], v[74:77]
	v_mfma_f32_16x16x32_bf16 v[78:81], v[94:97], v[8:11], v[78:81]
	s_waitcnt vmcnt(26)
	v_mfma_f32_16x16x32_bf16 v[74:77], v[98:101], v[12:15], v[74:77]
	v_mfma_f32_16x16x32_bf16 v[78:81], v[102:105], v[12:15], v[78:81]
	s_waitcnt vmcnt(24)
	v_mfma_f32_16x16x32_bf16 v[74:77], v[106:109], v[16:19], v[74:77]
	v_mfma_f32_16x16x32_bf16 v[78:81], v[110:113], v[16:19], v[78:81]
	s_waitcnt vmcnt(22)
	v_mfma_f32_16x16x32_bf16 v[74:77], v[114:117], v[20:23], v[74:77]
	v_mfma_f32_16x16x32_bf16 v[78:81], v[118:121], v[20:23], v[78:81]
	s_waitcnt vmcnt(20)
	v_mfma_f32_16x16x32_bf16 v[74:77], v[122:125], v[24:27], v[74:77]
	v_mfma_f32_16x16x32_bf16 v[78:81], v[126:129], v[24:27], v[78:81]
	s_waitcnt vmcnt(18)
	v_mfma_f32_16x16x32_bf16 v[74:77], v[130:133], v[28:31], v[74:77]
	v_mfma_f32_16x16x32_bf16 v[78:81], v[134:137], v[28:31], v[78:81]
	s_waitcnt vmcnt(16)
	v_mfma_f32_16x16x32_bf16 v[74:77], v[138:141], v[36:39], v[74:77]
	v_mfma_f32_16x16x32_bf16 v[78:81], v[142:145], v[36:39], v[78:81]
	s_waitcnt vmcnt(14)
	v_mfma_f32_16x16x32_bf16 v[74:77], v[146:149], v[40:43], v[74:77]
	v_mfma_f32_16x16x32_bf16 v[78:81], v[150:153], v[40:43], v[78:81]
	s_waitcnt vmcnt(12)
	v_mfma_f32_16x16x32_bf16 v[74:77], v[154:157], v[44:47], v[74:77]
	v_mfma_f32_16x16x32_bf16 v[78:81], v[158:161], v[44:47], v[78:81]
	s_waitcnt vmcnt(10)
	v_mfma_f32_16x16x32_bf16 v[74:77], v[162:165], v[48:51], v[74:77]
	v_mfma_f32_16x16x32_bf16 v[78:81], v[166:169], v[48:51], v[78:81]
	s_waitcnt vmcnt(8)
	v_mfma_f32_16x16x32_bf16 v[74:77], v[170:173], v[52:55], v[74:77]
	v_mfma_f32_16x16x32_bf16 v[78:81], v[174:177], v[52:55], v[78:81]
	s_waitcnt vmcnt(6)
	v_mfma_f32_16x16x32_bf16 v[74:77], v[178:181], v[56:59], v[74:77]
	v_mfma_f32_16x16x32_bf16 v[78:81], v[182:185], v[56:59], v[78:81]
	s_waitcnt vmcnt(4)
	v_mfma_f32_16x16x32_bf16 v[74:77], v[186:189], v[60:63], v[74:77]
	v_mfma_f32_16x16x32_bf16 v[78:81], v[190:193], v[60:63], v[78:81]
	s_waitcnt vmcnt(2)
	v_mfma_f32_16x16x32_bf16 v[74:77], v[194:197], v[246:249], v[74:77]
	v_mfma_f32_16x16x32_bf16 v[78:81], v[198:201], v[246:249], v[78:81]
	s_waitcnt vmcnt(0)
	v_mfma_f32_16x16x32_bf16 v[74:77], v[202:205], v[250:253], v[74:77]
	v_mfma_f32_16x16x32_bf16 v[78:81], v[206:209], v[250:253], v[78:81]
	s_nop 7
	ds_write_b128 v2, v[74:77]
	s_nop 0
	ds_write_b128 v2, v[78:81] offset:1024
	s_waitcnt lgkmcnt(0)
	s_waitcnt lgkmcnt(0)
	s_barrier
	s_cbranch_vccnz .LBB0_120
	global_load_dword v138, v[68:69], off
	ds_read_b128 v[74:77], v70
	ds_read_b128 v[78:81], v70 offset:1024
	ds_read_b128 v[82:85], v70 offset:2048
	ds_read_b128 v[86:89], v70 offset:3072
	ds_read_b128 v[90:93], v70 offset:4096
	ds_read_b128 v[94:97], v70 offset:5120
	ds_read_b128 v[98:101], v70 offset:6144
	ds_read_b128 v[102:105], v70 offset:7168
	ds_read_b128 v[106:109], v70 offset:8192
	ds_read_b128 v[110:113], v70 offset:9216
	ds_read_b128 v[114:117], v70 offset:10240
	ds_read_b128 v[118:121], v70 offset:11264
	ds_read_b128 v[122:125], v70 offset:12288
	ds_read_b128 v[126:129], v70 offset:13312
	ds_read_b128 v[130:133], v70 offset:14336
	ds_read_b128 v[134:137], v70 offset:15360
	s_waitcnt lgkmcnt(13)
	v_pk_add_f32 v[76:77], v[76:77], v[84:85]
	v_pk_add_f32 v[74:75], v[74:75], v[82:83]
	s_waitcnt lgkmcnt(12)
	v_pk_add_f32 v[78:79], v[78:79], v[86:87]
	s_waitcnt lgkmcnt(11)
	v_pk_add_f32 v[76:77], v[76:77], v[92:93]
	v_pk_add_f32 v[74:75], v[74:75], v[90:91]
	s_waitcnt lgkmcnt(10)
	v_pk_add_f32 v[78:79], v[78:79], v[94:95]
	s_waitcnt lgkmcnt(9)
	v_pk_add_f32 v[76:77], v[76:77], v[100:101]
	v_pk_add_f32 v[74:75], v[74:75], v[98:99]
	s_waitcnt lgkmcnt(8)
	v_pk_add_f32 v[78:79], v[78:79], v[102:103]
	s_waitcnt lgkmcnt(7)
	v_pk_add_f32 v[76:77], v[76:77], v[108:109]
	v_pk_add_f32 v[74:75], v[74:75], v[106:107]
	s_waitcnt lgkmcnt(6)
	v_pk_add_f32 v[78:79], v[78:79], v[110:111]
	s_waitcnt lgkmcnt(5)
	v_pk_add_f32 v[76:77], v[76:77], v[116:117]
	v_pk_add_f32 v[74:75], v[74:75], v[114:115]
	s_waitcnt lgkmcnt(4)
	v_pk_add_f32 v[78:79], v[78:79], v[118:119]
	s_waitcnt lgkmcnt(3)
	v_pk_add_f32 v[76:77], v[76:77], v[124:125]
	v_pk_add_f32 v[74:75], v[74:75], v[122:123]
	v_add_u32_e32 v2, s11, v71
	s_waitcnt lgkmcnt(2)
	v_pk_add_f32 v[78:79], v[78:79], v[126:127]
	s_waitcnt lgkmcnt(1)
	v_pk_add_f32 v[76:77], v[76:77], v[132:133]
	v_pk_add_f32 v[74:75], v[74:75], v[130:131]
	v_ashrrev_i32_e32 v73, 12, v2
	s_waitcnt lgkmcnt(0)
	v_pk_add_f32 v[78:79], v[78:79], v[134:135]
	v_mad_i64_i32 v[140:141], s[4:5], v73, s16, v[66:67]
	v_pk_add_f32 v[80:81], v[80:81], v[88:89]
	v_and_b32_e32 v2, 0xffc, v2
	v_pk_add_f32 v[80:81], v[80:81], v[96:97]
	v_lshlrev_b32_e32 v2, 1, v2
	v_pk_add_f32 v[80:81], v[80:81], v[104:105]
	s_waitcnt vmcnt(0)
	v_pk_mul_f32 v[76:77], v[76:77], v[138:139] op_sel_hi:[1,0]
	v_pk_mul_f32 v[74:75], v[74:75], v[138:139] op_sel_hi:[1,0]
	v_pk_mul_f32 v[78:79], v[78:79], v[138:139] op_sel_hi:[1,0]
	v_mul_f32_e32 v73, 0xbfb8aa3b, v74
	v_mul_f32_e32 v86, 0xbfb8aa3b, v75
	v_mul_f32_e32 v87, 0xbfb8aa3b, v76
	v_mul_f32_e32 v88, 0xbfb8aa3b, v77
	v_mov_b32_e32 v82, v74
	v_mov_b32_e32 v83, v76
	v_mov_b32_e32 v84, v78
	v_exp_f32_e32 v73, v73
	v_exp_f32_e32 v74, v86
	v_exp_f32_e32 v76, v87
	v_exp_f32_e32 v78, v88
	v_pk_add_f32 v[80:81], v[80:81], v[112:113]
	v_add_f32_e32 v73, 1.0, v73
	v_add_f32_e32 v74, 1.0, v74
	v_add_f32_e32 v76, 1.0, v76
	v_add_f32_e32 v78, 1.0, v78
	v_pk_add_f32 v[80:81], v[80:81], v[120:121]
	v_rcp_f32_e32 v86, v73
	v_rcp_f32_e32 v88, v74
	v_rcp_f32_e32 v87, v76
	v_rcp_f32_e32 v89, v78
	v_pk_add_f32 v[80:81], v[80:81], v[128:129]
	v_mov_b32_e32 v76, v75
	v_pk_add_f32 v[80:81], v[80:81], v[136:137]
	v_pk_mul_f32 v[74:75], v[82:83], v[86:87]
	v_pk_mul_f32 v[80:81], v[80:81], v[138:139] op_sel_hi:[1,0]
	v_pk_mul_f32 v[76:77], v[76:77], v[88:89]
	v_mov_b32_e32 v85, v80
	v_mov_b32_e32 v80, v79
	v_pk_mul_f32 v[74:75], v[84:85], v[74:75]
	v_pk_mul_f32 v[76:77], v[80:81], v[76:77]
	v_and_b32_sdwa v73, v75, v72 dst_sel:DWORD dst_unused:UNUSED_PAD src0_sel:WORD_1 src1_sel:DWORD
	v_and_b32_sdwa v79, v77, v72 dst_sel:DWORD dst_unused:UNUSED_PAD src0_sel:WORD_1 src1_sel:DWORD
	v_and_b32_sdwa v80, v76, v72 dst_sel:DWORD dst_unused:UNUSED_PAD src0_sel:WORD_1 src1_sel:DWORD
	v_and_b32_sdwa v78, v74, v72 dst_sel:DWORD dst_unused:UNUSED_PAD src0_sel:WORD_1 src1_sel:DWORD
	v_add3_u32 v73, v75, v73, s15
	v_add3_u32 v75, v77, v79, s15
	v_add3_u32 v76, v76, v80, s15
	v_add3_u32 v74, v74, v78, s15
	v_and_b32_e32 v75, 0xffff0000, v75
	v_and_b32_e32 v76, 0xffff0000, v76
	v_or_b32_sdwa v75, v75, v73 dst_sel:DWORD dst_unused:UNUSED_PAD src0_sel:DWORD src1_sel:WORD_1
	v_or_b32_sdwa v74, v76, v74 dst_sel:DWORD dst_unused:UNUSED_PAD src0_sel:DWORD src1_sel:WORD_1
	v_lshl_add_u64 v[76:77], v[140:141], 0, v[2:3]
	global_store_dwordx2 v[76:77], v[74:75], off
	s_branch .LBB0_120
